# P2/P9 tail GEMM: second column tile's weight rows requested together with the first (second LDS staging buffer), on top of v144
# baseline (speedup 1.0000x reference)
.LBB0_222:
	v_add_u32_e32 v32, s36, v40
	v_ashrrev_i32_e32 v33, 31, v32
	v_lshlrev_b64 v[32:33], 12, v[32:33]
	v_lshl_add_u64 v[48:49], v[36:37], 0, v[32:33]
	s_nop 0
	v_readfirstlane_b32 s100, v48
	v_readfirstlane_b32 s101, v49
	v_and_b32_e32 v132, 63, v171
	v_lshrrev_b32_e32 v133, 5, v132
	v_and_b32_e32 v134, 31, v132
	v_and_b32_e32 v135, 15, v132
	v_lshrrev_b32_e32 v136, 4, v132
	v_lshrrev_b32_e32 v137, 6, v171
	v_lshlrev_b32_e32 v137, 13, v137
	v_add_u32_e32 v137, 0x2000, v137
	s_nop 1
	v_readfirstlane_b32 s99, v137
	v_lshl_add_u32 v137, v135, 9, v137
	v_add_u32_e32 v138, 0, v133
	v_xor_b32_e32 v139, v134, v138
	v_mul_u32_u24_e32 v138, 0x1000, v138
	v_lshl_add_u32 v140, v139, 4, v138
	v_add_u32_e32 v138, 2, v133
	v_xor_b32_e32 v139, v134, v138
	v_mul_u32_u24_e32 v138, 0x1000, v138
	v_lshl_add_u32 v141, v139, 4, v138
	v_add_u32_e32 v138, 4, v133
	v_xor_b32_e32 v139, v134, v138
	v_mul_u32_u24_e32 v138, 0x1000, v138
	v_lshl_add_u32 v142, v139, 4, v138
	v_add_u32_e32 v138, 6, v133
	v_xor_b32_e32 v139, v134, v138
	v_mul_u32_u24_e32 v138, 0x1000, v138
	v_lshl_add_u32 v143, v139, 4, v138
	v_add_u32_e32 v138, 8, v133
	v_xor_b32_e32 v139, v134, v138
	v_mul_u32_u24_e32 v138, 0x1000, v138
	v_lshl_add_u32 v144, v139, 4, v138
	v_add_u32_e32 v138, 10, v133
	v_xor_b32_e32 v139, v134, v138
	v_mul_u32_u24_e32 v138, 0x1000, v138
	v_lshl_add_u32 v145, v139, 4, v138
	v_add_u32_e32 v138, 12, v133
	v_xor_b32_e32 v139, v134, v138
	v_mul_u32_u24_e32 v138, 0x1000, v138
	v_lshl_add_u32 v146, v139, 4, v138
	v_add_u32_e32 v138, 14, v133
	v_xor_b32_e32 v139, v134, v138
	v_mul_u32_u24_e32 v138, 0x1000, v138
	v_lshl_add_u32 v147, v139, 4, v138
	v_add_u32_e32 v138, 0, v136
	v_xor_b32_e32 v138, v138, v135
	v_lshl_add_u32 v148, v138, 4, v137
	v_add_u32_e32 v138, 4, v136
	v_xor_b32_e32 v138, v138, v135
	v_lshl_add_u32 v149, v138, 4, v137
	v_add_u32_e32 v138, 8, v136
	v_xor_b32_e32 v138, v138, v135
	v_lshl_add_u32 v150, v138, 4, v137
	v_add_u32_e32 v138, 12, v136
	v_xor_b32_e32 v138, v138, v135
	v_lshl_add_u32 v151, v138, 4, v137
	v_add_u32_e32 v138, 16, v136
	v_xor_b32_e32 v138, v138, v135
	v_lshl_add_u32 v152, v138, 4, v137
	v_add_u32_e32 v138, 20, v136
	v_xor_b32_e32 v138, v138, v135
	v_lshl_add_u32 v153, v138, 4, v137
	v_add_u32_e32 v138, 24, v136
	v_xor_b32_e32 v138, v138, v135
	v_lshl_add_u32 v154, v138, 4, v137
	v_add_u32_e32 v138, 28, v136
	v_xor_b32_e32 v138, v138, v135
	v_lshl_add_u32 v155, v138, 4, v137
	v_readlane_b32 s98, v250, 11
	s_cmp_lt_u32 s40, s98
	s_cbranch_scc1 .Ltd_k0_p2
	s_lshl_b32 s98, s98, 1
	s_cmp_lt_u32 s40, s98
	s_cbranch_scc1 .Ltd_k1_p2
	s_mov_b32 m0, s99
	s_nop 0
	global_load_lds_dwordx4 v140, s[100:101]
	s_add_u32 s99, s99, 0x400
	s_mov_b32 m0, s99
	s_nop 0
	global_load_lds_dwordx4 v141, s[100:101]
	s_add_u32 s99, s99, 0x400
	s_mov_b32 m0, s99
	s_nop 0
	global_load_lds_dwordx4 v142, s[100:101]
	s_add_u32 s99, s99, 0x400
	s_mov_b32 m0, s99
	s_nop 0
	global_load_lds_dwordx4 v143, s[100:101]
	s_add_u32 s99, s99, 0x400
	s_mov_b32 m0, s99
	s_nop 0
	global_load_lds_dwordx4 v144, s[100:101]
	s_add_u32 s99, s99, 0x400
	s_mov_b32 m0, s99
	s_nop 0
	global_load_lds_dwordx4 v145, s[100:101]
	s_add_u32 s99, s99, 0x400
	s_mov_b32 m0, s99
	s_nop 0
	global_load_lds_dwordx4 v146, s[100:101]
	s_add_u32 s99, s99, 0x400
	s_mov_b32 m0, s99
	s_nop 0
	global_load_lds_dwordx4 v147, s[100:101]
	s_branch .Ltd_rd_p2
.Ltd_k0_p2:
	s_mov_b32 m0, s99
	s_nop 0
	global_load_lds_dwordx4 v140, s[100:101]
	s_add_u32 s99, s99, 0x400
	s_mov_b32 m0, s99
	s_nop 0
	global_load_lds_dwordx4 v141, s[100:101]
	s_add_u32 s99, s99, 0x400
	s_mov_b32 m0, s99
	s_nop 0
	global_load_lds_dwordx4 v142, s[100:101]
	s_add_u32 s99, s99, 0x400
	s_mov_b32 m0, s99
	s_nop 0
	global_load_lds_dwordx4 v143, s[100:101]
	s_add_u32 s99, s99, 0x400
	s_mov_b32 m0, s99
	s_nop 0
	global_load_lds_dwordx4 v144, s[100:101]
	s_add_u32 s99, s99, 0x400
	s_mov_b32 m0, s99
	s_nop 0
	global_load_lds_dwordx4 v145, s[100:101]
	s_add_u32 s99, s99, 0x400
	s_mov_b32 m0, s99
	s_nop 0
	global_load_lds_dwordx4 v146, s[100:101]
	s_add_u32 s99, s99, 0x400
	s_mov_b32 m0, s99
	s_nop 0
	global_load_lds_dwordx4 v147, s[100:101]
	s_add_i32 s98, s40, s98
	s_cmpk_ge_i32 s98, 0x200
	s_cbranch_scc1 .Ltd_rd_p2
	v_readlane_b32 s98, v250, 11
	s_add_u32 s99, s99, 0xe400
	s_mul_i32 s98, s98, 0x10000
	s_add_u32 s100, s100, s98
	s_addc_u32 s101, s101, 0
	s_mov_b32 m0, s99
	s_nop 0
	global_load_lds_dwordx4 v140, s[100:101]
	s_add_u32 s99, s99, 0x400
	s_mov_b32 m0, s99
	s_nop 0
	global_load_lds_dwordx4 v141, s[100:101]
	s_add_u32 s99, s99, 0x400
	s_mov_b32 m0, s99
	s_nop 0
	global_load_lds_dwordx4 v142, s[100:101]
	s_add_u32 s99, s99, 0x400
	s_mov_b32 m0, s99
	s_nop 0
	global_load_lds_dwordx4 v143, s[100:101]
	s_add_u32 s99, s99, 0x400
	s_mov_b32 m0, s99
	s_nop 0
	global_load_lds_dwordx4 v144, s[100:101]
	s_add_u32 s99, s99, 0x400
	s_mov_b32 m0, s99
	s_nop 0
	global_load_lds_dwordx4 v145, s[100:101]
	s_add_u32 s99, s99, 0x400
	s_mov_b32 m0, s99
	s_nop 0
	global_load_lds_dwordx4 v146, s[100:101]
	s_add_u32 s99, s99, 0x400
	s_mov_b32 m0, s99
	s_nop 0
	global_load_lds_dwordx4 v147, s[100:101]
	s_branch .Ltd_rd_p2
.Ltd_k1_p2:
	v_add_u32_e32 v148, 0x10000, v148
	v_add_u32_e32 v149, 0x10000, v149
	v_add_u32_e32 v150, 0x10000, v150
	v_add_u32_e32 v151, 0x10000, v151
	v_add_u32_e32 v152, 0x10000, v152
	v_add_u32_e32 v153, 0x10000, v153
	v_add_u32_e32 v154, 0x10000, v154
	v_add_u32_e32 v155, 0x10000, v155
.Ltd_rd_p2:
	s_waitcnt vmcnt(0)
	ds_read_b128 v[100:103], v148
	ds_read_b128 v[104:107], v149
	ds_read_b128 v[108:111], v150
	ds_read_b128 v[112:115], v151
	ds_read_b128 v[116:119], v152
	ds_read_b128 v[120:123], v153
	ds_read_b128 v[124:127], v154
	ds_read_b128 v[128:131], v155
	s_waitcnt lgkmcnt(7)
	v_mfma_f32_16x16x32_bf16 v[32:35], v[100:103], v[24:27], 0
	s_waitcnt lgkmcnt(6)
	v_mfma_f32_16x16x32_bf16 v[32:35], v[104:107], v[0:3], v[32:35]
	s_waitcnt lgkmcnt(5)
	v_mfma_f32_16x16x32_bf16 v[32:35], v[108:111], v[4:7], v[32:35]
	s_waitcnt lgkmcnt(4)
	v_mfma_f32_16x16x32_bf16 v[32:35], v[112:115], v[8:11], v[32:35]
	s_waitcnt lgkmcnt(3)
	v_mfma_f32_16x16x32_bf16 v[32:35], v[116:119], v[12:15], v[32:35]
	s_waitcnt lgkmcnt(2)
	v_mfma_f32_16x16x32_bf16 v[32:35], v[120:123], v[16:19], v[32:35]
	s_waitcnt lgkmcnt(1)
	v_mfma_f32_16x16x32_bf16 v[32:35], v[124:127], v[20:23], v[32:35]
	s_waitcnt lgkmcnt(0)
	v_mfma_f32_16x16x32_bf16 v[32:35], v[128:131], v[28:31], v[32:35]
	s_nop 7
	ds_write_b128 v41, v[32:35]
	s_waitcnt lgkmcnt(0)
	s_barrier
	s_and_saveexec_b64 s[0:1], vcc
	s_cbranch_execz .LBB0_221
	ds_read_b128 v[44:47], v41 offset:1024
	ds_read_b128 v[48:51], v41 offset:2048
	ds_read_b128 v[52:55], v41 offset:3072
	ds_read_b128 v[56:59], v41 offset:4096
	s_waitcnt lgkmcnt(3)
	v_pk_add_f32 v[34:35], v[34:35], v[46:47]
	v_pk_add_f32 v[32:33], v[32:33], v[44:45]
	s_waitcnt lgkmcnt(2)
	v_pk_add_f32 v[34:35], v[34:35], v[50:51]
	v_pk_add_f32 v[32:33], v[32:33], v[48:49]
	s_waitcnt lgkmcnt(1)
	v_pk_add_f32 v[44:45], v[34:35], v[54:55]
	v_pk_add_f32 v[48:49], v[32:33], v[52:53]
	ds_read_b128 v[32:35], v41 offset:5120
	s_waitcnt lgkmcnt(1)
	v_pk_add_f32 v[52:53], v[44:45], v[58:59]
	ds_read_b128 v[44:47], v41 offset:6144
	v_pk_add_f32 v[54:55], v[48:49], v[56:57]
	ds_read_b128 v[48:51], v41 offset:7168
	s_waitcnt lgkmcnt(2)
	v_pk_add_f32 v[34:35], v[52:53], v[34:35]
	v_pk_add_f32 v[32:33], v[54:55], v[32:33]
	s_waitcnt lgkmcnt(1)
	v_pk_add_f32 v[34:35], v[34:35], v[46:47]
	v_pk_add_f32 v[32:33], v[32:33], v[44:45]
	v_add_u32_e32 v44, s36, v42
	s_waitcnt lgkmcnt(0)
	v_pk_add_f32 v[34:35], v[34:35], v[50:51]
	v_pk_add_f32 v[32:33], v[32:33], v[48:49]
	v_ashrrev_i32_e32 v45, 31, v44
	v_cvt_pk_bf16_f32 v32, v32, v33
	v_cvt_pk_bf16_f32 v33, v34, v35
	v_lshl_add_u64 v[34:35], v[44:45], 1, v[38:39]
	global_store_dwordx2 v[34:35], v[32:33], off
	s_branch .LBB0_221

.LBB0_1137:
	v_add_u32_e32 v32, s38, v40
	v_ashrrev_i32_e32 v33, 31, v32
	v_lshlrev_b64 v[32:33], 12, v[32:33]
	v_lshl_add_u64 v[48:49], v[36:37], 0, v[32:33]
	s_nop 0
	v_readfirstlane_b32 s100, v48
	v_readfirstlane_b32 s101, v49
	v_and_b32_e32 v132, 63, v171
	v_lshrrev_b32_e32 v133, 5, v132
	v_and_b32_e32 v134, 31, v132
	v_and_b32_e32 v135, 15, v132
	v_lshrrev_b32_e32 v136, 4, v132
	v_lshrrev_b32_e32 v137, 6, v171
	v_lshlrev_b32_e32 v137, 13, v137
	v_add_u32_e32 v137, 0x2000, v137
	s_nop 1
	v_readfirstlane_b32 s99, v137
	v_lshl_add_u32 v137, v135, 9, v137
	v_add_u32_e32 v138, 0, v133
	v_xor_b32_e32 v139, v134, v138
	v_mul_u32_u24_e32 v138, 0x1000, v138
	v_lshl_add_u32 v140, v139, 4, v138
	v_add_u32_e32 v138, 2, v133
	v_xor_b32_e32 v139, v134, v138
	v_mul_u32_u24_e32 v138, 0x1000, v138
	v_lshl_add_u32 v141, v139, 4, v138
	v_add_u32_e32 v138, 4, v133
	v_xor_b32_e32 v139, v134, v138
	v_mul_u32_u24_e32 v138, 0x1000, v138
	v_lshl_add_u32 v142, v139, 4, v138
	v_add_u32_e32 v138, 6, v133
	v_xor_b32_e32 v139, v134, v138
	v_mul_u32_u24_e32 v138, 0x1000, v138
	v_lshl_add_u32 v143, v139, 4, v138
	v_add_u32_e32 v138, 8, v133
	v_xor_b32_e32 v139, v134, v138
	v_mul_u32_u24_e32 v138, 0x1000, v138
	v_lshl_add_u32 v144, v139, 4, v138
	v_add_u32_e32 v138, 10, v133
	v_xor_b32_e32 v139, v134, v138
	v_mul_u32_u24_e32 v138, 0x1000, v138
	v_lshl_add_u32 v145, v139, 4, v138
	v_add_u32_e32 v138, 12, v133
	v_xor_b32_e32 v139, v134, v138
	v_mul_u32_u24_e32 v138, 0x1000, v138
	v_lshl_add_u32 v146, v139, 4, v138
	v_add_u32_e32 v138, 14, v133
	v_xor_b32_e32 v139, v134, v138
	v_mul_u32_u24_e32 v138, 0x1000, v138
	v_lshl_add_u32 v147, v139, 4, v138
	v_add_u32_e32 v138, 0, v136
	v_xor_b32_e32 v138, v138, v135
	v_lshl_add_u32 v148, v138, 4, v137
	v_add_u32_e32 v138, 4, v136
	v_xor_b32_e32 v138, v138, v135
	v_lshl_add_u32 v149, v138, 4, v137
	v_add_u32_e32 v138, 8, v136
	v_xor_b32_e32 v138, v138, v135
	v_lshl_add_u32 v150, v138, 4, v137
	v_add_u32_e32 v138, 12, v136
	v_xor_b32_e32 v138, v138, v135
	v_lshl_add_u32 v151, v138, 4, v137
	v_add_u32_e32 v138, 16, v136
	v_xor_b32_e32 v138, v138, v135
	v_lshl_add_u32 v152, v138, 4, v137
	v_add_u32_e32 v138, 20, v136
	v_xor_b32_e32 v138, v138, v135
	v_lshl_add_u32 v153, v138, 4, v137
	v_add_u32_e32 v138, 24, v136
	v_xor_b32_e32 v138, v138, v135
	v_lshl_add_u32 v154, v138, 4, v137
	v_add_u32_e32 v138, 28, v136
	v_xor_b32_e32 v138, v138, v135
	v_lshl_add_u32 v155, v138, 4, v137
	v_readlane_b32 s98, v250, 11
	s_cmp_lt_u32 s42, s98
	s_cbranch_scc1 .Ltd_k0_p9
	s_lshl_b32 s98, s98, 1
	s_cmp_lt_u32 s42, s98
	s_cbranch_scc1 .Ltd_k1_p9
	s_mov_b32 m0, s99
	s_nop 0
	global_load_lds_dwordx4 v140, s[100:101]
	s_add_u32 s99, s99, 0x400
	s_mov_b32 m0, s99
	s_nop 0
	global_load_lds_dwordx4 v141, s[100:101]
	s_add_u32 s99, s99, 0x400
	s_mov_b32 m0, s99
	s_nop 0
	global_load_lds_dwordx4 v142, s[100:101]
	s_add_u32 s99, s99, 0x400
	s_mov_b32 m0, s99
	s_nop 0
	global_load_lds_dwordx4 v143, s[100:101]
	s_add_u32 s99, s99, 0x400
	s_mov_b32 m0, s99
	s_nop 0
	global_load_lds_dwordx4 v144, s[100:101]
	s_add_u32 s99, s99, 0x400
	s_mov_b32 m0, s99
	s_nop 0
	global_load_lds_dwordx4 v145, s[100:101]
	s_add_u32 s99, s99, 0x400
	s_mov_b32 m0, s99
	s_nop 0
	global_load_lds_dwordx4 v146, s[100:101]
	s_add_u32 s99, s99, 0x400
	s_mov_b32 m0, s99
	s_nop 0
	global_load_lds_dwordx4 v147, s[100:101]
	s_branch .Ltd_rd_p9
.Ltd_k0_p9:
	s_mov_b32 m0, s99
	s_nop 0
	global_load_lds_dwordx4 v140, s[100:101]
	s_add_u32 s99, s99, 0x400
	s_mov_b32 m0, s99
	s_nop 0
	global_load_lds_dwordx4 v141, s[100:101]
	s_add_u32 s99, s99, 0x400
	s_mov_b32 m0, s99
	s_nop 0
	global_load_lds_dwordx4 v142, s[100:101]
	s_add_u32 s99, s99, 0x400
	s_mov_b32 m0, s99
	s_nop 0
	global_load_lds_dwordx4 v143, s[100:101]
	s_add_u32 s99, s99, 0x400
	s_mov_b32 m0, s99
	s_nop 0
	global_load_lds_dwordx4 v144, s[100:101]
	s_add_u32 s99, s99, 0x400
	s_mov_b32 m0, s99
	s_nop 0
	global_load_lds_dwordx4 v145, s[100:101]
	s_add_u32 s99, s99, 0x400
	s_mov_b32 m0, s99
	s_nop 0
	global_load_lds_dwordx4 v146, s[100:101]
	s_add_u32 s99, s99, 0x400
	s_mov_b32 m0, s99
	s_nop 0
	global_load_lds_dwordx4 v147, s[100:101]
	s_add_i32 s98, s42, s98
	s_cmpk_ge_i32 s98, 0x200
	s_cbranch_scc1 .Ltd_rd_p9
	v_readlane_b32 s98, v250, 11
	s_add_u32 s99, s99, 0xe400
	s_mul_i32 s98, s98, 0x10000
	s_add_u32 s100, s100, s98
	s_addc_u32 s101, s101, 0
	s_mov_b32 m0, s99
	s_nop 0
	global_load_lds_dwordx4 v140, s[100:101]
	s_add_u32 s99, s99, 0x400
	s_mov_b32 m0, s99
	s_nop 0
	global_load_lds_dwordx4 v141, s[100:101]
	s_add_u32 s99, s99, 0x400
	s_mov_b32 m0, s99
	s_nop 0
	global_load_lds_dwordx4 v142, s[100:101]
	s_add_u32 s99, s99, 0x400
	s_mov_b32 m0, s99
	s_nop 0
	global_load_lds_dwordx4 v143, s[100:101]
	s_add_u32 s99, s99, 0x400
	s_mov_b32 m0, s99
	s_nop 0
	global_load_lds_dwordx4 v144, s[100:101]
	s_add_u32 s99, s99, 0x400
	s_mov_b32 m0, s99
	s_nop 0
	global_load_lds_dwordx4 v145, s[100:101]
	s_add_u32 s99, s99, 0x400
	s_mov_b32 m0, s99
	s_nop 0
	global_load_lds_dwordx4 v146, s[100:101]
	s_add_u32 s99, s99, 0x400
	s_mov_b32 m0, s99
	s_nop 0
	global_load_lds_dwordx4 v147, s[100:101]
	s_branch .Ltd_rd_p9

.Ltd_rd_p9:
	s_waitcnt vmcnt(0)
	ds_read_b128 v[100:103], v148
	ds_read_b128 v[104:107], v149
	ds_read_b128 v[108:111], v150
	ds_read_b128 v[112:115], v151
	ds_read_b128 v[116:119], v152
	ds_read_b128 v[120:123], v153
	ds_read_b128 v[124:127], v154
	ds_read_b128 v[128:131], v155
	s_waitcnt lgkmcnt(7)
	v_mfma_f32_16x16x32_bf16 v[32:35], v[100:103], v[24:27], 0
	s_waitcnt lgkmcnt(6)
	v_mfma_f32_16x16x32_bf16 v[32:35], v[104:107], v[0:3], v[32:35]
	s_waitcnt lgkmcnt(5)
	v_mfma_f32_16x16x32_bf16 v[32:35], v[108:111], v[4:7], v[32:35]
	s_waitcnt lgkmcnt(4)
	v_mfma_f32_16x16x32_bf16 v[32:35], v[112:115], v[8:11], v[32:35]
	s_waitcnt lgkmcnt(3)
	v_mfma_f32_16x16x32_bf16 v[32:35], v[116:119], v[12:15], v[32:35]
	s_waitcnt lgkmcnt(2)
	v_mfma_f32_16x16x32_bf16 v[32:35], v[120:123], v[16:19], v[32:35]
	s_waitcnt lgkmcnt(1)
	v_mfma_f32_16x16x32_bf16 v[32:35], v[124:127], v[20:23], v[32:35]
	s_waitcnt lgkmcnt(0)
	v_mfma_f32_16x16x32_bf16 v[32:35], v[128:131], v[28:31], v[32:35]
	s_nop 7
	ds_write_b128 v41, v[32:35]
	s_waitcnt lgkmcnt(0)
	s_barrier
	s_and_saveexec_b64 s[0:1], vcc
	s_cbranch_execz .LBB0_1136
	ds_read_b128 v[44:47], v41 offset:1024
	s_waitcnt lgkmcnt(0)
	v_pk_add_f32 v[46:47], v[34:35], v[46:47]
	v_pk_add_f32 v[44:45], v[32:33], v[44:45]
	ds_read_b128 v[32:35], v41 offset:2048
	s_waitcnt lgkmcnt(0)
	v_pk_add_f32 v[46:47], v[46:47], v[34:35]
	v_pk_add_f32 v[44:45], v[44:45], v[32:33]
	ds_read_b128 v[32:35], v41 offset:3072
	s_waitcnt lgkmcnt(0)
	v_pk_add_f32 v[46:47], v[46:47], v[34:35]
	v_pk_add_f32 v[44:45], v[44:45], v[32:33]
	ds_read_b128 v[32:35], v41 offset:4096
	s_waitcnt lgkmcnt(0)
	v_pk_add_f32 v[46:47], v[46:47], v[34:35]
	v_pk_add_f32 v[44:45], v[44:45], v[32:33]
	ds_read_b128 v[32:35], v41 offset:5120
	s_waitcnt lgkmcnt(0)
	v_pk_add_f32 v[46:47], v[46:47], v[34:35]
	v_pk_add_f32 v[44:45], v[44:45], v[32:33]
	ds_read_b128 v[32:35], v41 offset:6144
	s_waitcnt lgkmcnt(0)
	v_pk_add_f32 v[46:47], v[46:47], v[34:35]
	v_pk_add_f32 v[44:45], v[44:45], v[32:33]
	ds_read_b128 v[32:35], v41 offset:7168
	s_waitcnt lgkmcnt(0)
	v_pk_add_f32 v[34:35], v[46:47], v[34:35]
	v_pk_add_f32 v[32:33], v[44:45], v[32:33]
	v_add_u32_e32 v44, s38, v42
	v_max_f32_e32 v32, 0, v32
	v_max_f32_e32 v33, 0, v33
	v_max_f32_e32 v34, 0, v34
	v_max_f32_e32 v35, 0, v35
	v_pk_mul_f32 v[32:33], v[32:33], v[32:33]
	v_pk_mul_f32 v[34:35], v[34:35], v[34:35]
	v_ashrrev_i32_e32 v45, 31, v44
	v_cvt_pk_bf16_f32 v32, v32, v33
	v_cvt_pk_bf16_f32 v33, v34, v35
	v_lshl_add_u64 v[34:35], v[44:45], 1, v[38:39]
	global_store_dwordx2 v[34:35], v[32:33], off
	s_branch .LBB0_1136
